# phase 4: late start of two s_sleep 127 for every other group of eight workgroups
# baseline (speedup 1.0000x reference)
.LBB0_577:
.LBB0_578:
	s_cmp_lt_i32 s68, 5
	s_cselect_b64 s[6:7], -1, 0
	v_readlane_b32 s72, v240, 0
	s_and_b64 s[14:15], s[6:7], s[4:5]
	v_readlane_b32 s73, v240, 1
	s_andn2_b64 vcc, exec, s[14:15]
	s_cbranch_vccnz .LBB0_629
	s_cmpk_lg_u32 s70, 0x100
	s_cbranch_scc1 .Lp4_go
	s_bitcmp1_b32 s2, 3
	s_cbranch_scc0 .Lp4_go
	s_sleep 127
	s_sleep 127
